# gdn chunk item: RAW staging loads issued at the item top, before the log-decay scan chain
# baseline (speedup 1.0000x reference)
; __device__ __forceinline__ void gdn_chunk_item(const Params& p, int item, char* smem) {
;     ...
;   __syncthreads();
;   if (tid < 64) {
;     float g = ((const float*)(ws + OFF_GLOG))[(size_t)(tok0 + tid) * 4 + h];
;     float bt = ((const float*)(ws + OFF_BETA))[(size_t)(tok0 + tid) * 4 + h];
;     float c = g;
; #pragma unroll
;     for (int o = 1; o < 64; o <<= 1) { float t = __shfl_up(c, o); if (lane >= o) c += t; }
;     sm_g[tid] = g; sm_bt[tid] = bt; sm_gc[tid] = c; sm_eg[tid] = __expf(c);
;   }
;   __syncthreads();
;   const float gl = sm_gc[63];
;   const int type = tid >> 7, c = tid & 127;
;   float val[64];
;   float vv[64];
;   {
;     u16* tile = (u16*)Xs;
;     for (int i = tid; i < 67 * 48; i += 256) {
;       const int row = i / 48, rem = i - row * 48, seg = rem >> 4, c8 = rem & 15;
;       uint4 v4 = make_uint4(0, 0, 0, 0);
;       if (n > 0 || row >= 3) v4 = *(const uint4*)(RAW + (size_t)(tok0 - 3 + row) * 1536 + seg * 512 + h * 128 + c8 * 8);
;       *(uint4*)&tile[row * 384 + seg * 128 + c8 * 8] = v4;
;     }
.LBB0_798:
	s_and_b32 s3, s84, 31
	s_lshl_b32 s0, s84, 4
	s_and_b32 s0, s0, 0xfffff800
	s_lshl_b32 s1, s3, 6
	v_readlane_b32 s4, v254, 52
	s_bfe_u32 s6, s84, 0x20005
	s_or_b32 s55, s0, s1
	s_cmp_lg_u32 s3, 0
	s_cselect_b64 s[98:99], -1, 0
	s_movk_i32 s36, 0xffd0
	s_movk_i32 s56, 0xc00
	v_mov_b32_e32 v3, s55
	v_add_u32_e32 v3, -3, v3
	v_mov_b64_e32 v[4:5], s[78:79]
	v_mov_b32_e32 v7, 0
	s_nop 0
	v_mad_i64_i32 v[4:5], vcc, v3, s56, v[4:5]
	s_lshl_b32 s56, s6, 8
	v_lshl_add_u64 v[4:5], v[4:5], 0, s[56:57]
	v_lshl_add_u64 v[4:5], v[4:5], 0, v[34:35]
	v_mov_b32_e32 v0, v237
	v_mul_u32_u24_e32 v1, 0xaaab, v0
	v_lshrrev_b32_e32 v1, 21, v1
	v_mad_i32_i24 v2, v1, s36, v0
	v_ashrrev_i32_e32 v2, 4, v2
	v_mul_u32_u24_e32 v3, 0xc00, v1
	v_lshl_add_u32 v6, v2, 10, v3
	v_lshl_add_u64 v[2:3], v[4:5], 0, v[6:7]
	v_accvgpr_write_b32 a196, 0
	v_accvgpr_write_b32 a197, 0
	v_accvgpr_write_b32 a198, 0
	v_accvgpr_write_b32 a199, 0
	v_cmp_lt_u32_e32 vcc, 0x8f, v0
	s_nop 1
	s_or_b64 vcc, s[98:99], vcc
	s_and_saveexec_b64 s[36:37], vcc
	global_load_dwordx4 a[196:199], v[2:3], off
	s_or_b64 exec, exec, s[36:37]
	s_movk_i32 s36, 0xffd0
	v_add_u32_e32 v0, 256, v237
	v_mul_u32_u24_e32 v1, 0xaaab, v0
	v_lshrrev_b32_e32 v1, 21, v1
	v_mad_i32_i24 v2, v1, s36, v0
	v_ashrrev_i32_e32 v2, 4, v2
	v_mul_u32_u24_e32 v3, 0xc00, v1
	v_lshl_add_u32 v6, v2, 10, v3
	v_lshl_add_u64 v[2:3], v[4:5], 0, v[6:7]
	global_load_dwordx4 a[200:203], v[2:3], off
	v_add_u32_e32 v0, 512, v237
	v_mul_u32_u24_e32 v1, 0xaaab, v0
	v_lshrrev_b32_e32 v1, 21, v1
	v_mad_i32_i24 v2, v1, s36, v0
	v_ashrrev_i32_e32 v2, 4, v2
	v_mul_u32_u24_e32 v3, 0xc00, v1
	v_lshl_add_u32 v6, v2, 10, v3
	v_lshl_add_u64 v[2:3], v[4:5], 0, v[6:7]
	global_load_dwordx4 a[204:207], v[2:3], off
	v_add_u32_e32 v0, 768, v237
	v_mul_u32_u24_e32 v1, 0xaaab, v0
	v_lshrrev_b32_e32 v1, 21, v1
	v_mad_i32_i24 v2, v1, s36, v0
	v_ashrrev_i32_e32 v2, 4, v2
	v_mul_u32_u24_e32 v3, 0xc00, v1
	v_lshl_add_u32 v6, v2, 10, v3
	v_lshl_add_u64 v[2:3], v[4:5], 0, v[6:7]
	global_load_dwordx4 a[208:211], v[2:3], off
	v_add_u32_e32 v0, 1024, v237
	v_mul_u32_u24_e32 v1, 0xaaab, v0
	v_lshrrev_b32_e32 v1, 21, v1
	v_mad_i32_i24 v2, v1, s36, v0
	v_ashrrev_i32_e32 v2, 4, v2
	v_mul_u32_u24_e32 v3, 0xc00, v1
	v_lshl_add_u32 v6, v2, 10, v3
	v_lshl_add_u64 v[2:3], v[4:5], 0, v[6:7]
	global_load_dwordx4 a[212:215], v[2:3], off
	v_add_u32_e32 v0, 1280, v237
	v_mul_u32_u24_e32 v1, 0xaaab, v0
	v_lshrrev_b32_e32 v1, 21, v1
	v_mad_i32_i24 v2, v1, s36, v0
	v_ashrrev_i32_e32 v2, 4, v2
	v_mul_u32_u24_e32 v3, 0xc00, v1
	v_lshl_add_u32 v6, v2, 10, v3
	v_lshl_add_u64 v[2:3], v[4:5], 0, v[6:7]
	global_load_dwordx4 a[216:219], v[2:3], off
	v_add_u32_e32 v0, 1536, v237
	v_mul_u32_u24_e32 v1, 0xaaab, v0
	v_lshrrev_b32_e32 v1, 21, v1
	v_mad_i32_i24 v2, v1, s36, v0
	v_ashrrev_i32_e32 v2, 4, v2
	v_mul_u32_u24_e32 v3, 0xc00, v1
	v_lshl_add_u32 v6, v2, 10, v3
	v_lshl_add_u64 v[2:3], v[4:5], 0, v[6:7]
	global_load_dwordx4 a[220:223], v[2:3], off
	v_add_u32_e32 v0, 1792, v237
	v_mul_u32_u24_e32 v1, 0xaaab, v0
	v_lshrrev_b32_e32 v1, 21, v1
	v_mad_i32_i24 v2, v1, s36, v0
	v_ashrrev_i32_e32 v2, 4, v2
	v_mul_u32_u24_e32 v3, 0xc00, v1
	v_lshl_add_u32 v6, v2, 10, v3
	v_lshl_add_u64 v[2:3], v[4:5], 0, v[6:7]
	global_load_dwordx4 a[224:227], v[2:3], off
	v_add_u32_e32 v0, 2048, v237
	v_mul_u32_u24_e32 v1, 0xaaab, v0
	v_lshrrev_b32_e32 v1, 21, v1
	v_mad_i32_i24 v2, v1, s36, v0
	v_ashrrev_i32_e32 v2, 4, v2
	v_mul_u32_u24_e32 v3, 0xc00, v1
	v_lshl_add_u32 v6, v2, 10, v3
	v_lshl_add_u64 v[2:3], v[4:5], 0, v[6:7]
	global_load_dwordx4 a[228:231], v[2:3], off
	v_add_u32_e32 v0, 2304, v237
	v_mul_u32_u24_e32 v1, 0xaaab, v0
	v_lshrrev_b32_e32 v1, 21, v1
	v_mad_i32_i24 v2, v1, s36, v0
	v_ashrrev_i32_e32 v2, 4, v2
	v_mul_u32_u24_e32 v3, 0xc00, v1
	v_lshl_add_u32 v6, v2, 10, v3
	v_lshl_add_u64 v[2:3], v[4:5], 0, v[6:7]
	global_load_dwordx4 a[232:235], v[2:3], off
	v_add_u32_e32 v0, 2560, v237
	v_mul_u32_u24_e32 v1, 0xaaab, v0
	v_lshrrev_b32_e32 v1, 21, v1
	v_mad_i32_i24 v2, v1, s36, v0
	v_ashrrev_i32_e32 v2, 4, v2
	v_mul_u32_u24_e32 v3, 0xc00, v1
	v_lshl_add_u32 v6, v2, 10, v3
	v_lshl_add_u64 v[2:3], v[4:5], 0, v[6:7]
	global_load_dwordx4 a[236:239], v[2:3], off
	v_add_u32_e32 v0, 2816, v237
	v_mul_u32_u24_e32 v1, 0xaaab, v0
	v_lshrrev_b32_e32 v1, 21, v1
	v_mad_i32_i24 v2, v1, s36, v0
	v_ashrrev_i32_e32 v2, 4, v2
	v_mul_u32_u24_e32 v3, 0xc00, v1
	v_lshl_add_u32 v6, v2, 10, v3
	v_lshl_add_u64 v[2:3], v[4:5], 0, v[6:7]
	global_load_dwordx4 a[240:243], v[2:3], off
	v_add_u32_e32 v0, 3072, v237
	v_mul_u32_u24_e32 v1, 0xaaab, v0
	v_lshrrev_b32_e32 v1, 21, v1
	v_mad_i32_i24 v2, v1, s36, v0
	v_ashrrev_i32_e32 v2, 4, v2
	v_mul_u32_u24_e32 v3, 0xc00, v1
	v_lshl_add_u32 v6, v2, 10, v3
	v_lshl_add_u64 v[2:3], v[4:5], 0, v[6:7]
	v_cmp_gt_u32_e32 vcc, 0x90, v237
	s_nop 1
	s_and_saveexec_b64 s[36:37], vcc
	global_load_dwordx4 a[244:247], v[2:3], off
	s_or_b64 exec, exec, s[36:37]
	s_movk_i32 s36, 0xffd0
	v_readlane_b32 s5, v254, 53
	s_barrier
	s_and_saveexec_b64 s[0:1], s[4:5]
	s_cbranch_execz .LBB0_800
	v_or_b32_e32 v0, s55, v237
	v_ashrrev_i32_e32 v1, 31, v0
	v_lshlrev_b64 v[0:1], 4, v[0:1]
	v_readlane_b32 s4, v254, 38
	v_lshl_or_b32 v0, s6, 2, v0
	v_readlane_b32 s5, v254, 39
	s_nop 1
	v_lshl_add_u64 v[2:3], s[4:5], 0, v[0:1]
	global_load_dword v2, v[2:3], off
	v_readlane_b32 s4, v254, 36
	v_readlane_b32 s5, v254, 37
	s_nop 1
	v_lshl_add_u64 v[0:1], s[4:5], 0, v[0:1]
	global_load_dword v0, v[0:1], off
	v_accvgpr_read_b32 v1, a104
	v_readlane_b32 s4, v254, 54
	v_readlane_b32 s5, v254, 55
	v_accvgpr_read_b32 v3, a105
	s_waitcnt vmcnt(1)
	ds_bpermute_b32 v1, v1, v2
	s_waitcnt lgkmcnt(0)
	v_add_f32_e32 v1, v2, v1
	v_cndmask_b32_e64 v1, v1, v2, s[4:5]
	ds_bpermute_b32 v3, v3, v1
	v_readlane_b32 s4, v254, 56
	v_readlane_b32 s5, v254, 57
	s_waitcnt lgkmcnt(0)
	v_add_f32_e32 v3, v1, v3
	v_cndmask_b32_e64 v1, v3, v1, s[4:5]
	v_accvgpr_read_b32 v3, a106
	ds_bpermute_b32 v3, v3, v1
	v_readlane_b32 s4, v254, 58
	v_readlane_b32 s5, v254, 59
	s_waitcnt lgkmcnt(0)
	v_add_f32_e32 v3, v1, v3
	v_cndmask_b32_e64 v1, v3, v1, s[4:5]
	v_accvgpr_read_b32 v3, a107
	ds_bpermute_b32 v3, v3, v1
	v_readlane_b32 s4, v254, 60
	v_readlane_b32 s5, v254, 61
	s_waitcnt lgkmcnt(0)
	v_add_f32_e32 v3, v1, v3
	v_cndmask_b32_e64 v1, v3, v1, s[4:5]
	v_accvgpr_read_b32 v3, a108
	ds_bpermute_b32 v3, v3, v1
	v_readlane_b32 s4, v254, 62
	v_readlane_b32 s5, v254, 63
	s_waitcnt lgkmcnt(0)
	v_add_f32_e32 v3, v1, v3
	v_cndmask_b32_e64 v1, v3, v1, s[4:5]
	v_accvgpr_read_b32 v3, a109
	ds_bpermute_b32 v3, v3, v1
	s_waitcnt lgkmcnt(0)
	v_add_f32_e32 v3, v1, v3
	v_cndmask_b32_e64 v1, v3, v1, s[18:19]
	v_mul_f32_e32 v3, 0x3fb8aa3b, v1
	v_exp_f32_e32 v3, v3
	s_waitcnt vmcnt(0)
	ds_write2st64_b32 v32, v2, v0 offset0:252 offset1:253
	ds_write2st64_b32 v32, v1, v3 offset0:254 offset1:255
; __device__ __forceinline__ void gdn_chunk_item(const Params& p, int item, char* smem) {
;     ...
;   __syncthreads();
;   const float gl = sm_gc[63];
;   const int type = tid >> 7, c = tid & 127;
;   float val[64];
;   float vv[64];
;   {
;     u16* tile = (u16*)Xs;
;     for (int i = tid; i < 67 * 48; i += 256) {
;       const int row = i / 48, rem = i - row * 48, seg = rem >> 4, c8 = rem & 15;
;       uint4 v4 = make_uint4(0, 0, 0, 0);
;       if (n > 0 || row >= 3) v4 = *(const uint4*)(RAW + (size_t)(tok0 - 3 + row) * 1536 + seg * 512 + h * 128 + c8 * 8);
;       *(uint4*)&tile[row * 384 + seg * 128 + c8 * 8] = v4;
;     }
.LBB0_800:
	s_or_b64 exec, exec, s[0:1]
	s_waitcnt lgkmcnt(0)
	s_barrier
	ds_read_b32 v235, v35 offset:65276
	s_cmp_lg_u32 s3, 0
	s_cselect_b64 s[0:1], -1, 0
	s_add_i32 s3, s55, -3
	s_lshl_b32 s72, s6, 7
	s_mov_b64 s[6:7], 0
	v_lshlrev_b32_e32 v6, 4, v240
	s_waitcnt vmcnt(0)
	v_mov_b32_e32 v0, v237
	v_mul_u32_u24_e32 v1, 0xaaab, v0
	v_lshrrev_b32_e32 v1, 21, v1
	v_mad_i32_i24 v2, v1, s36, v0
	v_ashrrev_i32_e32 v2, 4, v2
	v_lshlrev_b32_e32 v2, 8, v2
	v_mul_u32_u24_e32 v1, 0x300, v1
	v_add3_u32 v1, v1, v2, v6
	v_add_u32_e32 v1, 0x10400, v1
	ds_write_b128 v1, a[196:199]
	v_add_u32_e32 v0, 256, v237
	v_mul_u32_u24_e32 v1, 0xaaab, v0
	v_lshrrev_b32_e32 v1, 21, v1
	v_mad_i32_i24 v2, v1, s36, v0
	v_ashrrev_i32_e32 v2, 4, v2
	v_lshlrev_b32_e32 v2, 8, v2
	v_mul_u32_u24_e32 v1, 0x300, v1
	v_add3_u32 v1, v1, v2, v6
	v_add_u32_e32 v1, 0x10400, v1
	ds_write_b128 v1, a[200:203]
	v_add_u32_e32 v0, 512, v237
	v_mul_u32_u24_e32 v1, 0xaaab, v0
	v_lshrrev_b32_e32 v1, 21, v1
	v_mad_i32_i24 v2, v1, s36, v0
	v_ashrrev_i32_e32 v2, 4, v2
	v_lshlrev_b32_e32 v2, 8, v2
	v_mul_u32_u24_e32 v1, 0x300, v1
	v_add3_u32 v1, v1, v2, v6
	v_add_u32_e32 v1, 0x10400, v1
	ds_write_b128 v1, a[204:207]
	v_add_u32_e32 v0, 768, v237
	v_mul_u32_u24_e32 v1, 0xaaab, v0
	v_lshrrev_b32_e32 v1, 21, v1
	v_mad_i32_i24 v2, v1, s36, v0
	v_ashrrev_i32_e32 v2, 4, v2
	v_lshlrev_b32_e32 v2, 8, v2
	v_mul_u32_u24_e32 v1, 0x300, v1
	v_add3_u32 v1, v1, v2, v6
	v_add_u32_e32 v1, 0x10400, v1
	ds_write_b128 v1, a[208:211]
	v_add_u32_e32 v0, 1024, v237
	v_mul_u32_u24_e32 v1, 0xaaab, v0
	v_lshrrev_b32_e32 v1, 21, v1
	v_mad_i32_i24 v2, v1, s36, v0
	v_ashrrev_i32_e32 v2, 4, v2
	v_lshlrev_b32_e32 v2, 8, v2
	v_mul_u32_u24_e32 v1, 0x300, v1
	v_add3_u32 v1, v1, v2, v6
	v_add_u32_e32 v1, 0x10400, v1
	ds_write_b128 v1, a[212:215]
	v_add_u32_e32 v0, 1280, v237
	v_mul_u32_u24_e32 v1, 0xaaab, v0
	v_lshrrev_b32_e32 v1, 21, v1
	v_mad_i32_i24 v2, v1, s36, v0
	v_ashrrev_i32_e32 v2, 4, v2
	v_lshlrev_b32_e32 v2, 8, v2
	v_mul_u32_u24_e32 v1, 0x300, v1
	v_add3_u32 v1, v1, v2, v6
	v_add_u32_e32 v1, 0x10400, v1
	ds_write_b128 v1, a[216:219]
	v_add_u32_e32 v0, 1536, v237
	v_mul_u32_u24_e32 v1, 0xaaab, v0
	v_lshrrev_b32_e32 v1, 21, v1
	v_mad_i32_i24 v2, v1, s36, v0
	v_ashrrev_i32_e32 v2, 4, v2
	v_lshlrev_b32_e32 v2, 8, v2
	v_mul_u32_u24_e32 v1, 0x300, v1
	v_add3_u32 v1, v1, v2, v6
	v_add_u32_e32 v1, 0x10400, v1
	ds_write_b128 v1, a[220:223]
	v_add_u32_e32 v0, 1792, v237
	v_mul_u32_u24_e32 v1, 0xaaab, v0
	v_lshrrev_b32_e32 v1, 21, v1
	v_mad_i32_i24 v2, v1, s36, v0
	v_ashrrev_i32_e32 v2, 4, v2
	v_lshlrev_b32_e32 v2, 8, v2
	v_mul_u32_u24_e32 v1, 0x300, v1
	v_add3_u32 v1, v1, v2, v6
	v_add_u32_e32 v1, 0x10400, v1
	ds_write_b128 v1, a[224:227]
	v_add_u32_e32 v0, 2048, v237
	v_mul_u32_u24_e32 v1, 0xaaab, v0
	v_lshrrev_b32_e32 v1, 21, v1
	v_mad_i32_i24 v2, v1, s36, v0
	v_ashrrev_i32_e32 v2, 4, v2
	v_lshlrev_b32_e32 v2, 8, v2
	v_mul_u32_u24_e32 v1, 0x300, v1
	v_add3_u32 v1, v1, v2, v6
	v_add_u32_e32 v1, 0x10400, v1
	ds_write_b128 v1, a[228:231]
	v_add_u32_e32 v0, 2304, v237
	v_mul_u32_u24_e32 v1, 0xaaab, v0
	v_lshrrev_b32_e32 v1, 21, v1
	v_mad_i32_i24 v2, v1, s36, v0
	v_ashrrev_i32_e32 v2, 4, v2
	v_lshlrev_b32_e32 v2, 8, v2
	v_mul_u32_u24_e32 v1, 0x300, v1
	v_add3_u32 v1, v1, v2, v6
	v_add_u32_e32 v1, 0x10400, v1
	ds_write_b128 v1, a[232:235]
	v_add_u32_e32 v0, 2560, v237
	v_mul_u32_u24_e32 v1, 0xaaab, v0
	v_lshrrev_b32_e32 v1, 21, v1
	v_mad_i32_i24 v2, v1, s36, v0
	v_ashrrev_i32_e32 v2, 4, v2
	v_lshlrev_b32_e32 v2, 8, v2
	v_mul_u32_u24_e32 v1, 0x300, v1
	v_add3_u32 v1, v1, v2, v6
	v_add_u32_e32 v1, 0x10400, v1
	ds_write_b128 v1, a[236:239]
	v_add_u32_e32 v0, 2816, v237
	v_mul_u32_u24_e32 v1, 0xaaab, v0
	v_lshrrev_b32_e32 v1, 21, v1
	v_mad_i32_i24 v2, v1, s36, v0
	v_ashrrev_i32_e32 v2, 4, v2
	v_lshlrev_b32_e32 v2, 8, v2
	v_mul_u32_u24_e32 v1, 0x300, v1
	v_add3_u32 v1, v1, v2, v6
	v_add_u32_e32 v1, 0x10400, v1
	ds_write_b128 v1, a[240:243]
	v_add_u32_e32 v0, 3072, v237
	v_mul_u32_u24_e32 v1, 0xaaab, v0
	v_lshrrev_b32_e32 v1, 21, v1
	v_mad_i32_i24 v2, v1, s36, v0
	v_ashrrev_i32_e32 v2, 4, v2
	v_lshlrev_b32_e32 v2, 8, v2
	v_mul_u32_u24_e32 v1, 0x300, v1
	v_add3_u32 v1, v1, v2, v6
	v_add_u32_e32 v1, 0x10400, v1
	v_cmp_gt_u32_e32 vcc, 0x90, v237
	s_nop 1
	s_and_saveexec_b64 s[36:37], vcc
	ds_write_b128 v1, a[244:247]
	s_or_b64 exec, exec, s[36:37]
	s_mov_b64 s[6:7], exec
